# GLA mix_a items: own gate inputs (lr rows, w_up^T, bias) fetched one item ahead into spare registers; head waits count past the fresh prefetch
# baseline (speedup 1.0000x reference)
.LBB0_1294:
	s_waitcnt lgkmcnt(0)
	s_add_u32 s26, s18, 0x7a00000
	s_addc_u32 s27, s19, 0
	s_add_u32 s28, s18, 0x32c0000
	s_addc_u32 s29, s19, 0
	s_add_u32 s30, s16, 0x4000000
	s_addc_u32 s31, s17, 0
	s_add_u32 s36, s18, 0x14a00000
	v_mov_b32_e32 v9, 0
	s_addc_u32 s37, s19, 0
	v_mov_b32_e32 v10, v9
	v_mov_b32_e32 v11, v9
	s_add_u32 s0, s18, 0x3800000
	v_mov_b32_e32 v8, v9
	v_mov_b64_e32 v[26:27], v[10:11]
	v_mov_b64_e32 v[30:31], v[10:11]
	v_mov_b64_e32 v[38:39], v[10:11]
	v_mov_b64_e32 v[42:43], v[10:11]
	v_mov_b64_e32 v[46:47], v[10:11]
	v_mov_b64_e32 v[50:51], v[10:11]
	s_addc_u32 s1, s19, 0
	s_mov_b32 s39, 0
	s_movk_i32 s20, 0x1a00
	s_mov_b32 s21, 0x7a01000
	s_mov_b32 s33, 0x7a1b000
	s_mov_b32 s34, 0x7a35000
	s_mov_b32 s35, 0x7a4f000
	s_movk_i32 s42, 0x220
	s_mov_b32 s43, 0xbfb8aa3b
	s_mov_b32 s46, 0x3f317218
	s_mov_b32 s50, 0x3d800000
	s_movk_i32 s44, 0x80
	s_movk_i32 s45, 0x120
	v_mov_b32_e32 v102, 0x1a00
	v_mov_b32_e32 v103, 0x4400
	s_mov_b32 s47, s3
	s_mov_b32 s2, s97
	v_mov_b64_e32 v[24:25], v[8:9]
	v_mov_b64_e32 v[28:29], v[8:9]
	v_mov_b64_e32 v[36:37], v[8:9]
	v_mov_b64_e32 v[40:41], v[8:9]
	v_mov_b64_e32 v[44:45], v[8:9]
	v_mov_b64_e32 v[48:49], v[8:9]
	s_mov_b32 s82, 1
	v_mov_b32_e32 v212, 0
	v_mov_b32_e32 v213, 0
	v_mov_b32_e32 v214, 0
	v_mov_b32_e32 v215, 0
	v_mov_b32_e32 v216, 0
	v_mov_b32_e32 v217, 0
	v_mov_b32_e32 v218, 0
	v_mov_b32_e32 v219, 0
	v_mov_b32_e32 v220, 0
	v_mov_b32_e32 v221, 0
	v_mov_b32_e32 v222, 0
	v_mov_b32_e32 v223, 0
	v_mov_b32_e32 v224, 0
	v_mov_b32_e32 v225, 0
	v_mov_b32_e32 v226, 0
	v_mov_b32_e32 v227, 0
	v_mov_b32_e32 v228, 0
	v_mov_b32_e32 v229, 0
	v_mov_b32_e32 v230, 0
	v_mov_b32_e32 v231, 0
	v_mov_b32_e32 v232, 0
	v_mov_b32_e32 v233, 0
	v_mov_b32_e32 v234, 0
	v_mov_b32_e32 v235, 0
	v_mov_b32_e32 v240, 0
	v_mov_b32_e32 v241, 0
	v_mov_b32_e32 v242, 0
	v_mov_b32_e32 v243, 0
	v_mov_b32_e32 v248, 0
	v_mov_b32_e32 v249, 0
	v_mov_b32_e32 v250, 0
	v_mov_b32_e32 v251, 0
	s_branch .LBB0_1297

.LBB0_1299:
.Lgp9a_top:
	s_cmp_eq_u32 s82, 1
	s_cbranch_scc1 .Lgp9a_z
	s_add_i32 s32, s2, s22
	s_cmpk_gt_i32 s32, 0x3ff
	s_cbranch_scc1 .Lgp9a_last
	s_ashr_i32 s98, s32, 8
	s_ashr_i32 s99, s2, 8
	s_sub_i32 s98, s98, s99
	s_lshl_b32 s98, s98, 12
	s_and_b32 s99, s32, 63
	s_and_b32 s100, s2, 63
	s_sub_i32 s99, s99, s100
	s_lshl_b32 s99, s99, 6
	s_add_i32 s98, s98, s99
	s_mul_i32 s78, s98, 0x1a00
	s_ashr_i32 s79, s78, 31
	s_bfe_u32 s98, s32, 0x20006
	s_bfe_u32 s99, s2, 0x20006
	s_sub_i32 s98, s98, s99
	s_lshl_b32 s84, s98, 12
	s_ashr_i32 s85, s84, 31
	s_lshl_b32 s86, s98, 9
	s_ashr_i32 s87, s86, 31
	s_waitcnt vmcnt(22)
	s_branch .Lgp9a_go
.Lgp9a_last:
	s_waitcnt vmcnt(16)
.Lgp9a_z:
	s_mov_b64 s[78:79], 0
	s_mov_b64 s[84:85], 0
	s_mov_b64 s[86:87], 0
.Lgp9a_go:
	s_ashr_i32 s12, s2, 8
	s_and_b32 s51, s2, 63
	s_ashr_i32 s13, s12, 31
	v_mov_b32_e32 v10, v204
	s_lshl_b64 s[10:11], s[12:13], 12
	s_lshl_b32 s13, s51, 6
	s_or_b32 s10, s10, s13
	v_and_b32_e32 v92, 15, v10
	v_or_b32_e32 v8, s10, v92
	v_mov_b64_e32 v[52:53], s[18:19]
	v_mad_u64_u32 v[52:53], s[14:15], v8, s20, v[52:53]
	v_mad_i32_i24 v53, s11, v102, v53
	v_and_b32_e32 v8, 48, v10
	v_lshl_add_u64 v[52:53], v[52:53], 0, v[8:9]
	v_add_co_u32_e32 v54, vcc, s21, v52
	s_bfe_u32 s13, s2, 0x20006
	s_nop 0
	v_addc_co_u32_e32 v55, vcc, 0, v53, vcc
	v_add_co_u32_e32 v56, vcc, s33, v52
	s_lshl_b32 s16, s13, 7
	s_nop 0
	v_addc_co_u32_e32 v57, vcc, 0, v53, vcc
	v_lshl_add_u64 v[246:247], v[54:55], 0, s[78:79]
	v_mov_b32_e32 v72, v212
	v_mov_b32_e32 v73, v213
	v_mov_b32_e32 v74, v214
	v_mov_b32_e32 v75, v215
	global_load_dwordx4 v[212:215], v[246:247], off offset:2048
	v_lshl_add_u64 v[244:245], v[56:57], 0, s[78:79]
	v_mov_b32_e32 v68, v216
	v_mov_b32_e32 v69, v217
	v_mov_b32_e32 v70, v218
	v_mov_b32_e32 v71, v219
	global_load_dwordx4 v[216:219], v[244:245], off offset:2048
	v_add_co_u32_e32 v54, vcc, s34, v52
	v_ashrrev_i32_e32 v11, 2, v10
	s_nop 0
	v_addc_co_u32_e32 v55, vcc, 0, v53, vcc
	v_add_co_u32_e32 v52, vcc, s35, v52
	v_and_b32_e32 v58, -16, v11
	s_nop 0
	v_addc_co_u32_e32 v53, vcc, 0, v53, vcc
	v_lshl_add_u64 v[246:247], v[54:55], 0, s[78:79]
	v_mov_b32_e32 v60, v220
	v_mov_b32_e32 v61, v221
	v_mov_b32_e32 v62, v222
	v_mov_b32_e32 v63, v223
	global_load_dwordx4 v[220:223], v[246:247], off offset:2048
	s_nop 0
	v_lshl_add_u64 v[244:245], v[52:53], 0, s[78:79]
	v_mov_b32_e32 v52, v224
	v_mov_b32_e32 v53, v225
	v_mov_b32_e32 v54, v226
	v_mov_b32_e32 v55, v227
	global_load_dwordx4 v[224:227], v[244:245], off offset:2048
	v_or_b32_e32 v11, s16, v92
	v_and_b32_e32 v94, 63, v10
	v_add_u32_e32 v64, v11, v58
	v_and_b32_e32 v56, 16, v10
	v_mov_b32_e32 v57, v9
	v_lshl_add_u64 v[66:67], s[28:29], 0, v[56:57]
	v_cmp_lt_u32_e32 vcc, 31, v94
	v_cmp_gt_u32_e64 s[10:11], 32, v94
	v_mov_b32_e32 v56, 0
	v_ashrrev_i32_e32 v65, 31, v64
	v_mov_b32_e32 v76, 0
	v_mov_b32_e32 v77, 0
	v_mov_b32_e32 v78, 0
	v_mov_b32_e32 v79, 0
	s_and_saveexec_b64 s[14:15], s[10:11]
	s_cbranch_execz .LBB0_1301
	v_lshlrev_b64 v[76:77], 5, v[64:65]
	v_lshl_add_u64 v[76:77], v[66:67], 0, v[76:77]
	v_lshl_add_u64 v[246:247], v[76:77], 0, s[84:85]
	v_mov_b32_e32 v76, v228
	v_mov_b32_e32 v77, v229
	v_mov_b32_e32 v78, v230
	v_mov_b32_e32 v79, v231
	global_load_dwordx4 v[228:231], v[246:247], off
.LBB0_1301:
	s_or_b64 exec, exec, s[14:15]
	s_lshl_b32 s10, s16, 2
	s_add_u32 s10, s24, s10
	v_bfe_u32 v93, v10, 4, 2
	s_addc_u32 s11, s25, 0
	v_ashrrev_i32_e32 v59, 31, v58
	v_lshl_add_u64 v[58:59], v[58:59], 2, s[10:11]
	v_lshlrev_b32_e32 v80, 4, v93
	v_mov_b32_e32 v81, v9
	v_lshl_add_u64 v[84:85], v[58:59], 0, v[80:81]
	v_lshl_add_u64 v[244:245], v[84:85], 0, s[86:87]
	v_mov_b32_e32 v80, v232
	v_mov_b32_e32 v81, v233
	v_mov_b32_e32 v82, v234
	v_mov_b32_e32 v83, v235
	global_load_dwordx4 v[232:235], v[244:245], off
	v_mov_b32_e32 v57, 0
	v_mov_b32_e32 v58, 0
	v_mov_b32_e32 v59, 0
	s_and_saveexec_b64 s[10:11], vcc
	s_cbranch_execz .LBB0_1303
	v_lshlrev_b64 v[56:57], 5, v[64:65]
	v_lshl_add_u64 v[56:57], v[66:67], 0, v[56:57]
	v_add_co_u32_e32 v56, vcc, 0x4000, v56
	s_nop 1
	v_addc_co_u32_e32 v57, vcc, 0, v57, vcc
	v_lshl_add_u64 v[246:247], v[56:57], 0, s[84:85]
	v_mov_b32_e32 v56, v240
	v_mov_b32_e32 v57, v241
	v_mov_b32_e32 v58, v242
	v_mov_b32_e32 v59, v243
	global_load_dwordx4 v[240:243], v[246:247], off
.LBB0_1303:
	s_or_b64 exec, exec, s[10:11]
	v_lshl_add_u64 v[244:245], v[84:85], 0, s[86:87]
	v_mov_b32_e32 v64, v248
	v_mov_b32_e32 v65, v249
	v_mov_b32_e32 v66, v250
	v_mov_b32_e32 v67, v251
	global_load_dwordx4 v[248:251], v[244:245], off offset:2048
	s_cmp_eq_u32 s82, 1
	s_cbranch_scc0 .Lgp9a_d
	s_mov_b32 s82, 0
	s_waitcnt vmcnt(0)
	s_branch .Lgp9a_top
.Lgp9a_d:
	v_ashrrev_i32_e32 v11, 31, v10
	v_lshrrev_b32_e32 v84, 27, v11
	v_add_u32_e32 v84, v10, v84
	v_lshrrev_b32_e32 v85, 5, v84
	v_and_b32_e32 v84, 0xfffffe0, v84
	v_sub_u32_e32 v84, v10, v84
	v_mul_lo_u32 v85, v85, s42
	v_lshlrev_b32_e32 v84, 4, v84
	v_add3_u32 v84, 0, v85, v84
	s_nop 0
	ds_write_b128 v84, v[0:3] offset:51200
	v_add_u32_e32 v84, 0x200, v10
	v_ashrrev_i32_e32 v85, 31, v84
	v_lshrrev_b32_e32 v85, 27, v85
	v_add_u32_e32 v85, v84, v85
	v_lshrrev_b32_e32 v86, 5, v85
	v_and_b32_e32 v85, 0xfffffe0, v85
	v_sub_u32_e32 v84, v84, v85
	v_mul_lo_u32 v85, v86, s42
	v_lshlrev_b32_e32 v84, 4, v84
	v_add3_u32 v84, 0, v85, v84
	s_nop 0
	ds_write_b128 v84, v[4:7] offset:51200
	v_add_u32_e32 v84, 0x400, v10
	v_ashrrev_i32_e32 v85, 31, v84
	v_lshrrev_b32_e32 v85, 27, v85
	v_add_u32_e32 v85, v84, v85
	v_lshrrev_b32_e32 v86, 5, v85
	v_and_b32_e32 v85, 0xfffffe0, v85
	v_sub_u32_e32 v84, v84, v85
	v_mul_lo_u32 v85, v86, s42
	v_lshlrev_b32_e32 v84, 4, v84
	v_add3_u32 v84, 0, v85, v84
	s_nop 0
	ds_write_b128 v84, v[12:15] offset:51200
	v_add_u32_e32 v84, 0x600, v10
	v_ashrrev_i32_e32 v85, 31, v84
	v_lshrrev_b32_e32 v85, 27, v85
	v_add_u32_e32 v85, v84, v85
	v_lshrrev_b32_e32 v86, 5, v85
	v_and_b32_e32 v85, 0xfffffe0, v85
	v_sub_u32_e32 v84, v84, v85
	s_lshl_b32 s10, s12, 3
	s_lshl_b32 s11, s13, 1
	v_mul_lo_u32 v85, v86, s42
	v_lshlrev_b32_e32 v84, 4, v84
	s_or_b32 s52, s11, s10
	v_add3_u32 v84, 0, v85, v84
	s_cmp_gt_i32 s52, 44
	s_mov_b64 s[10:11], -1
	s_nop 0
	ds_write_b128 v84, v[16:19] offset:51200
	s_cbranch_scc0 .LBB0_1309
	s_cmp_gt_u32 s52, 60
	s_cbranch_scc0 .LBB0_1306
	s_sub_i32 s38, s52, 61
	s_mov_b64 s[10:11], 0
	s_mov_b64 s[54:55], s[18:19]
	s_mov_b64 s[56:57], s[38:39]

.LBB0_1311:
	v_lshlrev_b32_e32 v86, 2, v10
	v_and_b32_e32 v87, 0x1fc, v86
	v_add_u32_e32 v104, 0, v87
	v_add_u32_e32 v107, s92, v86
	v_add_u32_e32 v106, s92, v87
	s_nop 0
	v_mfma_f32_16x16x32_bf16 v[86:89], v[76:79], v[72:75], 0
	v_lshlrev_b32_e32 v84, 9, v92
	v_and_b32_e32 v85, 0xffffffc0, v10
	v_add3_u32 v85, 0, v84, v85
	v_add_u32_e32 v108, v85, v8
	v_ashrrev_i32_e32 v84, 7, v10
	s_nop 0
	s_nop 1
	v_add_f32_e32 v90, v80, v86
	v_add_f32_e32 v87, v81, v87
	v_min_f32_e32 v86, 0, v90
	v_mul_f32_e64 v90, |v90|, s43
	v_mul_f32_e64 v91, |v87|, s43
	v_add_f32_e32 v95, v82, v88
	v_add_f32_e32 v89, v83, v89
	v_exp_f32_e32 v90, v90
	v_exp_f32_e32 v91, v91
	v_min_f32_e32 v88, 0, v95
	v_mul_f32_e64 v95, |v95|, s43
	v_mul_f32_e64 v96, |v89|, s43
	v_exp_f32_e32 v95, v95
	v_exp_f32_e32 v96, v96
	v_add_f32_e32 v90, 1.0, v90
	v_add_f32_e32 v91, 1.0, v91
	v_log_f32_e32 v90, v90
	v_log_f32_e32 v91, v91
	v_add_f32_e32 v95, 1.0, v95
	v_add_f32_e32 v96, 1.0, v96
	v_log_f32_e32 v95, v95
	v_log_f32_e32 v96, v96
	v_min_f32_e32 v87, 0, v87
	v_xor_b32_e32 v91, 0x80000000, v91
	v_xor_b32_e32 v90, 0x80000000, v90
	v_min_f32_e32 v89, 0, v89
	v_pk_fma_f32 v[86:87], v[90:91], s[46:47], v[86:87] op_sel_hi:[1,0,1]
	v_xor_b32_e32 v91, 0x80000000, v96
	v_xor_b32_e32 v90, 0x80000000, v95
	v_pk_fma_f32 v[88:89], v[90:91], s[46:47], v[88:89] op_sel_hi:[1,0,1]
	v_pk_mul_f32 v[86:87], v[86:87], s[50:51] op_sel_hi:[1,0]
	v_pk_mul_f32 v[88:89], v[88:89], s[50:51] op_sel_hi:[1,0]
	ds_write_b128 v108, v[86:89]
	v_mfma_f32_16x16x32_bf16 v[86:89], v[76:79], v[68:71], 0
	v_lshlrev_b32_e32 v105, 13, v84
	v_cmp_lt_i32_e64 s[10:11], 0, v84
	v_mov_b32_e32 v117, 0
	s_nop 4
	v_add_f32_e32 v85, v81, v87
	v_mul_f32_e64 v87, |v85|, s43
	v_exp_f32_e32 v90, v87
	v_add_f32_e32 v8, v80, v86
	v_min_f32_e32 v87, 0, v85
	v_min_f32_e32 v86, 0, v8
	v_add_f32_e32 v85, 1.0, v90
	v_add_f32_e32 v90, v82, v88
	v_mul_f32_e64 v8, |v8|, s43
	v_min_f32_e32 v88, 0, v90
	v_mul_f32_e64 v90, |v90|, s43
	v_add_f32_e32 v89, v83, v89
	v_exp_f32_e32 v8, v8
	v_exp_f32_e32 v90, v90
	v_mul_f32_e64 v91, |v89|, s43
	v_exp_f32_e32 v91, v91
	v_add_f32_e32 v8, 1.0, v8
	v_add_f32_e32 v90, 1.0, v90
	v_log_f32_e32 v8, v8
	v_log_f32_e32 v85, v85
	v_log_f32_e32 v95, v90
	v_add_f32_e32 v90, 1.0, v91
	v_log_f32_e32 v96, v90
	v_xor_b32_e32 v91, 0x80000000, v85
	v_xor_b32_e32 v90, 0x80000000, v8
	v_min_f32_e32 v89, 0, v89
	v_pk_fma_f32 v[86:87], v[90:91], s[46:47], v[86:87] op_sel_hi:[1,0,1]
	v_xor_b32_e32 v91, 0x80000000, v96
	v_xor_b32_e32 v90, 0x80000000, v95
	v_pk_fma_f32 v[88:89], v[90:91], s[46:47], v[88:89] op_sel_hi:[1,0,1]
	v_pk_mul_f32 v[86:87], v[86:87], s[50:51] op_sel_hi:[1,0]
	v_pk_mul_f32 v[88:89], v[88:89], s[50:51] op_sel_hi:[1,0]
	ds_write_b128 v108, v[86:89] offset:8192
	v_mfma_f32_16x16x32_bf16 v[86:89], v[76:79], v[60:63], 0
	v_mfma_f32_16x16x32_bf16 v[76:79], v[76:79], v[52:55], 0
	s_nop 6
	v_add_f32_e32 v85, v81, v87
	v_mul_f32_e64 v87, |v85|, s43
	v_exp_f32_e32 v90, v87
	v_add_f32_e32 v8, v80, v86
	v_min_f32_e32 v86, 0, v8
	v_mul_f32_e64 v8, |v8|, s43
	v_exp_f32_e32 v8, v8
	v_min_f32_e32 v87, 0, v85
	v_add_f32_e32 v85, 1.0, v90
	v_add_f32_e32 v90, v82, v88
	v_min_f32_e32 v88, 0, v90
	v_mul_f32_e64 v90, |v90|, s43
	v_add_f32_e32 v89, v83, v89
	v_exp_f32_e32 v90, v90
	v_mul_f32_e64 v91, |v89|, s43
	v_add_f32_e32 v8, 1.0, v8
	v_exp_f32_e32 v91, v91
	v_log_f32_e32 v8, v8
	v_add_f32_e32 v90, 1.0, v90
	v_log_f32_e32 v95, v90
	v_add_f32_e32 v90, 1.0, v91
	v_log_f32_e32 v96, v90
	v_xor_b32_e32 v90, 0x80000000, v8
	v_add_f32_e32 v8, v80, v76
	v_add_f32_e32 v77, v81, v77
	v_add_f32_e32 v81, v82, v78
	v_min_f32_e32 v76, 0, v8
	v_mul_f32_e64 v8, |v8|, s43
	v_mul_f32_e64 v80, |v77|, s43
	v_min_f32_e32 v78, 0, v81
	v_mul_f32_e64 v81, |v81|, s43
	v_add_f32_e32 v79, v83, v79
	v_exp_f32_e32 v8, v8
	v_exp_f32_e32 v80, v80
	v_exp_f32_e32 v81, v81
	v_mul_f32_e64 v82, |v79|, s43
	v_exp_f32_e32 v82, v82
	v_add_f32_e32 v8, 1.0, v8
	v_add_f32_e32 v80, 1.0, v80
	v_add_f32_e32 v81, 1.0, v81
	v_log_f32_e32 v85, v85
	v_log_f32_e32 v8, v8
	v_log_f32_e32 v80, v80
	v_log_f32_e32 v83, v81
	v_add_f32_e32 v81, 1.0, v82
	v_log_f32_e32 v82, v81
	v_xor_b32_e32 v91, 0x80000000, v85
	v_min_f32_e32 v77, 0, v77
	v_xor_b32_e32 v81, 0x80000000, v80
	v_xor_b32_e32 v80, 0x80000000, v8
	v_min_f32_e32 v89, 0, v89
	v_pk_fma_f32 v[86:87], v[90:91], s[46:47], v[86:87] op_sel_hi:[1,0,1]
	v_xor_b32_e32 v91, 0x80000000, v96
	v_xor_b32_e32 v90, 0x80000000, v95
	v_min_f32_e32 v79, 0, v79
	v_pk_fma_f32 v[76:77], v[80:81], s[46:47], v[76:77] op_sel_hi:[1,0,1]
	v_xor_b32_e32 v81, 0x80000000, v82
	v_xor_b32_e32 v80, 0x80000000, v83
	v_pk_fma_f32 v[88:89], v[90:91], s[46:47], v[88:89] op_sel_hi:[1,0,1]
	v_pk_fma_f32 v[78:79], v[80:81], s[46:47], v[78:79] op_sel_hi:[1,0,1]
	v_pk_mul_f32 v[88:89], v[88:89], s[50:51] op_sel_hi:[1,0]
	v_pk_mul_f32 v[86:87], v[86:87], s[50:51] op_sel_hi:[1,0]
	v_pk_mul_f32 v[78:79], v[78:79], s[50:51] op_sel_hi:[1,0]
	v_pk_mul_f32 v[76:77], v[76:77], s[50:51] op_sel_hi:[1,0]
	v_add_u32_e32 v8, v104, v105
	ds_write_b128 v108, v[86:89] offset:16384
	ds_write_b128 v108, v[76:79] offset:24576
	s_waitcnt lgkmcnt(0)
	s_barrier
	ds_read2st64_b32 v[76:77], v8 offset1:2
	ds_read2st64_b32 v[78:79], v8 offset0:4 offset1:6
	ds_read2st64_b32 v[80:81], v8 offset0:8 offset1:10
	ds_read2st64_b32 v[82:83], v8 offset0:12 offset1:14
	ds_read2st64_b32 v[86:87], v8 offset0:16 offset1:18
	ds_read2st64_b32 v[88:89], v8 offset0:20 offset1:22
	ds_read2st64_b32 v[90:91], v8 offset0:24 offset1:26
	ds_read2st64_b32 v[118:119], v8 offset0:28 offset1:30
	s_waitcnt lgkmcnt(7)
	v_add_f32_e32 v115, 0, v76
	v_add_f32_e32 v116, v115, v77
	s_waitcnt lgkmcnt(6)
	v_add_f32_e32 v113, v116, v78
	v_add_f32_e32 v114, v113, v79
	s_waitcnt lgkmcnt(5)
	v_add_f32_e32 v111, v114, v80
	v_add_f32_e32 v112, v111, v81
	s_waitcnt lgkmcnt(4)
	v_add_f32_e32 v101, v112, v82
	v_add_f32_e32 v109, v101, v83
	s_waitcnt lgkmcnt(3)
	v_add_f32_e32 v99, v109, v86
	v_add_f32_e32 v100, v99, v87
	s_waitcnt lgkmcnt(2)
	v_add_f32_e32 v97, v100, v88
	v_add_f32_e32 v98, v97, v89
	s_waitcnt lgkmcnt(1)
	v_add_f32_e32 v95, v98, v90
	v_add_f32_e32 v96, v95, v91
	s_waitcnt lgkmcnt(0)
	v_add_f32_e32 v90, v96, v118
	v_add_f32_e32 v91, v90, v119
	ds_write_b32 v107, v91
	s_waitcnt lgkmcnt(0)
	s_barrier
	s_and_saveexec_b64 s[12:13], s[10:11]
	s_cbranch_execnz .LBB0_1366
	s_or_b64 exec, exec, s[12:13]
	v_cmp_lt_i32_e64 s[14:15], 1, v84
	s_and_saveexec_b64 s[12:13], s[14:15]
	s_cbranch_execnz .LBB0_1367

.LBB0_1334:
.Lgp9b_top:
	s_cmp_eq_u32 s82, 1
	s_cbranch_scc1 .Lgp9b_z
	s_add_i32 s32, s48, s22
	s_cmpk_gt_i32 s32, 0x3ff
	s_cbranch_scc1 .Lgp9b_last
	s_ashr_i32 s98, s32, 8
	s_ashr_i32 s99, s48, 8
	s_sub_i32 s98, s98, s99
	s_lshl_b32 s98, s98, 12
	s_and_b32 s99, s32, 63
	s_and_b32 s100, s48, 63
	s_sub_i32 s99, s99, s100
	s_lshl_b32 s99, s99, 6
	s_add_i32 s98, s98, s99
	s_mul_i32 s78, s98, 0x1a00
	s_ashr_i32 s79, s78, 31
	s_bfe_u32 s98, s32, 0x20006
	s_bfe_u32 s99, s48, 0x20006
	s_sub_i32 s98, s98, s99
	s_lshl_b32 s84, s98, 12
	s_ashr_i32 s85, s84, 31
	s_lshl_b32 s86, s98, 9
	s_ashr_i32 s87, s86, 31
	s_waitcnt vmcnt(22)
	s_branch .Lgp9b_go

.Lgp9b_go:
	s_ashr_i32 s12, s48, 8
	s_and_b32 s49, s48, 63
	s_ashr_i32 s13, s12, 31
	v_mov_b32_e32 v10, v204
	s_lshl_b64 s[10:11], s[12:13], 12
	s_lshl_b32 s2, s49, 6
	s_or_b32 s2, s10, s2
	v_and_b32_e32 v92, 15, v10
	v_or_b32_e32 v8, s2, v92
	v_mov_b64_e32 v[52:53], s[18:19]
	v_mad_u64_u32 v[52:53], s[14:15], v8, s20, v[52:53]
	v_mad_i32_i24 v53, s11, v102, v53
	v_and_b32_e32 v8, 48, v10
	v_lshl_add_u64 v[52:53], v[52:53], 0, v[8:9]
	v_add_co_u32_e32 v54, vcc, s21, v52
	s_bfe_u32 s2, s48, 0x20006
	s_nop 0
	v_addc_co_u32_e32 v55, vcc, 0, v53, vcc
	v_add_co_u32_e32 v56, vcc, s33, v52
	s_lshl_b32 s13, s2, 7
	s_nop 0
	v_addc_co_u32_e32 v57, vcc, 0, v53, vcc
	v_lshl_add_u64 v[246:247], v[54:55], 0, s[78:79]
	v_mov_b32_e32 v72, v212
	v_mov_b32_e32 v73, v213
	v_mov_b32_e32 v74, v214
	v_mov_b32_e32 v75, v215
	global_load_dwordx4 v[212:215], v[246:247], off offset:2048
	v_lshl_add_u64 v[244:245], v[56:57], 0, s[78:79]
	v_mov_b32_e32 v68, v216
	v_mov_b32_e32 v69, v217
	v_mov_b32_e32 v70, v218
	v_mov_b32_e32 v71, v219
	global_load_dwordx4 v[216:219], v[244:245], off offset:2048
	v_add_co_u32_e32 v54, vcc, s34, v52
	v_ashrrev_i32_e32 v11, 2, v10
	s_nop 0
	v_addc_co_u32_e32 v55, vcc, 0, v53, vcc
	v_add_co_u32_e32 v52, vcc, s35, v52
	v_and_b32_e32 v58, -16, v11
	s_nop 0
	v_addc_co_u32_e32 v53, vcc, 0, v53, vcc
	v_lshl_add_u64 v[246:247], v[54:55], 0, s[78:79]
	v_mov_b32_e32 v60, v220
	v_mov_b32_e32 v61, v221
	v_mov_b32_e32 v62, v222
	v_mov_b32_e32 v63, v223
	global_load_dwordx4 v[220:223], v[246:247], off offset:2048
	s_nop 0
	v_lshl_add_u64 v[244:245], v[52:53], 0, s[78:79]
	v_mov_b32_e32 v52, v224
	v_mov_b32_e32 v53, v225
	v_mov_b32_e32 v54, v226
	v_mov_b32_e32 v55, v227
	global_load_dwordx4 v[224:227], v[244:245], off offset:2048
	v_or_b32_e32 v11, s13, v92
	v_and_b32_e32 v94, 63, v10
	v_add_u32_e32 v64, v11, v58
	v_and_b32_e32 v56, 16, v10
	v_mov_b32_e32 v57, v9
	v_lshl_add_u64 v[66:67], s[28:29], 0, v[56:57]
	v_cmp_lt_u32_e32 vcc, 31, v94
	v_cmp_gt_u32_e64 s[10:11], 32, v94
	v_mov_b32_e32 v56, 0
	v_ashrrev_i32_e32 v65, 31, v64
	v_mov_b32_e32 v76, 0
	v_mov_b32_e32 v77, 0
	v_mov_b32_e32 v78, 0
	v_mov_b32_e32 v79, 0
	s_and_saveexec_b64 s[14:15], s[10:11]
	s_cbranch_execz .LBB0_1336
	v_lshlrev_b64 v[76:77], 5, v[64:65]
	v_lshl_add_u64 v[76:77], v[66:67], 0, v[76:77]
	v_lshl_add_u64 v[246:247], v[76:77], 0, s[84:85]
	v_mov_b32_e32 v76, v228
	v_mov_b32_e32 v77, v229
	v_mov_b32_e32 v78, v230
	v_mov_b32_e32 v79, v231
	global_load_dwordx4 v[228:231], v[246:247], off
.LBB0_1336:
	s_or_b64 exec, exec, s[14:15]
	s_lshl_b32 s10, s13, 2
	s_add_u32 s10, s24, s10
	v_bfe_u32 v93, v10, 4, 2
	s_addc_u32 s11, s25, 0
	v_ashrrev_i32_e32 v59, 31, v58
	v_lshl_add_u64 v[58:59], v[58:59], 2, s[10:11]
	v_lshlrev_b32_e32 v80, 4, v93
	v_mov_b32_e32 v81, v9
	v_lshl_add_u64 v[84:85], v[58:59], 0, v[80:81]
	v_lshl_add_u64 v[244:245], v[84:85], 0, s[86:87]
	v_mov_b32_e32 v80, v232
	v_mov_b32_e32 v81, v233
	v_mov_b32_e32 v82, v234
	v_mov_b32_e32 v83, v235
	global_load_dwordx4 v[232:235], v[244:245], off
	v_mov_b32_e32 v57, 0
	v_mov_b32_e32 v58, 0
	v_mov_b32_e32 v59, 0
	s_and_saveexec_b64 s[10:11], vcc
	s_cbranch_execz .LBB0_1338
	v_lshlrev_b64 v[56:57], 5, v[64:65]
	v_lshl_add_u64 v[56:57], v[66:67], 0, v[56:57]
	v_add_co_u32_e32 v56, vcc, 0x4000, v56
	s_nop 1
	v_addc_co_u32_e32 v57, vcc, 0, v57, vcc
	v_lshl_add_u64 v[246:247], v[56:57], 0, s[84:85]
	v_mov_b32_e32 v56, v240
	v_mov_b32_e32 v57, v241
	v_mov_b32_e32 v58, v242
	v_mov_b32_e32 v59, v243
	global_load_dwordx4 v[240:243], v[246:247], off

.Lgp9b_d:
	v_ashrrev_i32_e32 v11, 31, v10
	v_lshrrev_b32_e32 v84, 27, v11
	v_add_u32_e32 v84, v10, v84
	v_lshrrev_b32_e32 v85, 5, v84
	v_and_b32_e32 v84, 0xfffffe0, v84
	v_sub_u32_e32 v84, v10, v84
	v_mul_lo_u32 v85, v85, s42
	v_lshlrev_b32_e32 v84, 4, v84
	v_add3_u32 v84, 0, v85, v84
	ds_write_b128 v84, v[24:27] offset:51200
	v_add_u32_e32 v84, 0x200, v10
	v_ashrrev_i32_e32 v85, 31, v84
	v_lshrrev_b32_e32 v85, 27, v85
	v_add_u32_e32 v85, v84, v85
	v_lshrrev_b32_e32 v86, 5, v85
	v_and_b32_e32 v85, 0xfffffe0, v85
	v_sub_u32_e32 v84, v84, v85
	v_mul_lo_u32 v85, v86, s42
	v_lshlrev_b32_e32 v84, 4, v84
	v_add3_u32 v84, 0, v85, v84
	ds_write_b128 v84, v[28:31] offset:51200
	v_add_u32_e32 v84, 0x400, v10
	v_ashrrev_i32_e32 v85, 31, v84
	v_lshrrev_b32_e32 v85, 27, v85
	v_add_u32_e32 v85, v84, v85
	v_lshrrev_b32_e32 v86, 5, v85
	v_and_b32_e32 v85, 0xfffffe0, v85
	v_sub_u32_e32 v84, v84, v85
	v_mul_lo_u32 v85, v86, s42
	v_lshlrev_b32_e32 v84, 4, v84
	v_add3_u32 v84, 0, v85, v84
	ds_write_b128 v84, v[36:39] offset:51200
	v_add_u32_e32 v84, 0x600, v10
	v_ashrrev_i32_e32 v85, 31, v84
	v_lshrrev_b32_e32 v85, 27, v85
	v_add_u32_e32 v85, v84, v85
	v_lshrrev_b32_e32 v86, 5, v85
	v_and_b32_e32 v85, 0xfffffe0, v85
	v_sub_u32_e32 v84, v84, v85
	s_lshl_b32 s10, s12, 3
	s_lshl_b32 s2, s2, 1
	v_mul_lo_u32 v85, v86, s42
	v_lshlrev_b32_e32 v84, 4, v84
	s_or_b32 s52, s2, s10
	v_add3_u32 v84, 0, v85, v84
	s_cmp_gt_i32 s52, 44
	s_mov_b64 s[10:11], -1
	ds_write_b128 v84, v[40:43] offset:51200
	s_cbranch_scc0 .LBB0_1344
	s_cmp_gt_u32 s52, 60
	s_cbranch_scc0 .LBB0_1341
	s_sub_i32 s38, s52, 61
	s_mov_b64 s[10:11], 0
	s_mov_b64 s[54:55], s[18:19]
	s_mov_b64 s[56:57], s[38:39]

.LBB0_1432:
	s_waitcnt lgkmcnt(0)
	s_lshr_b32 s2, s2, 16
	s_and_b32 s2, 0xffff, s2
	s_cmp_lg_u32 s2, 0
	s_cselect_b64 s[10:11], -1, 0
	v_cndmask_b32_e64 v0, 0, 1, s[10:11]
	s_cmp_lg_u64 s[10:11], 0
	v_readfirstlane_b32 s2, v0
	s_addc_u32 s66, s22, 0
	s_lshl_b32 s10, s2, 1
	v_mov_b32_e32 v2, v1
	v_mov_b32_e32 v3, v1
	s_add_i32 s67, s89, s10
	s_lshl_b32 s10, s2, 7
	s_lshl_b32 s2, s2, 6
	v_mov_b32_e32 v0, v1
	s_waitcnt vmcnt(0)
	v_mov_b64_e32 v[22:23], v[2:3]
	v_mov_b64_e32 v[26:27], v[2:3]
	v_mov_b64_e32 v[38:39], v[2:3]
	v_mov_b64_e32 v[42:43], v[2:3]
	v_mov_b64_e32 v[46:47], v[2:3]
	v_mov_b64_e32 v[50:51], v[2:3]
	s_add_i32 s68, s88, s10
	s_add_i32 s69, s90, s2
	s_mov_b32 s70, s3
	s_mov_b32 s2, s97
	v_mov_b64_e32 v[20:21], v[0:1]
	v_mov_b64_e32 v[24:25], v[0:1]
	v_mov_b64_e32 v[36:37], v[0:1]
	v_mov_b64_e32 v[40:41], v[0:1]
	v_mov_b64_e32 v[44:45], v[0:1]
	v_mov_b64_e32 v[48:49], v[0:1]
	s_mov_b32 s82, 1
	v_mov_b32_e32 v212, 0
	v_mov_b32_e32 v213, 0
	v_mov_b32_e32 v214, 0
	v_mov_b32_e32 v215, 0
	v_mov_b32_e32 v216, 0
	v_mov_b32_e32 v217, 0
	v_mov_b32_e32 v218, 0
	v_mov_b32_e32 v219, 0
	v_mov_b32_e32 v220, 0
	v_mov_b32_e32 v221, 0
	v_mov_b32_e32 v222, 0
	v_mov_b32_e32 v223, 0
	v_mov_b32_e32 v224, 0
	v_mov_b32_e32 v225, 0
	v_mov_b32_e32 v226, 0
	v_mov_b32_e32 v227, 0
	v_mov_b32_e32 v228, 0
	v_mov_b32_e32 v229, 0
	v_mov_b32_e32 v230, 0
	v_mov_b32_e32 v231, 0
	v_mov_b32_e32 v232, 0
	v_mov_b32_e32 v233, 0
	v_mov_b32_e32 v234, 0
	v_mov_b32_e32 v235, 0
	v_mov_b32_e32 v240, 0
	v_mov_b32_e32 v241, 0
	v_mov_b32_e32 v242, 0
	v_mov_b32_e32 v243, 0
	v_mov_b32_e32 v248, 0
	v_mov_b32_e32 v249, 0
	v_mov_b32_e32 v250, 0
	v_mov_b32_e32 v251, 0
	s_branch .LBB0_1435

.LBB0_1437:
.Lgp10a_top:
	s_cmp_eq_u32 s82, 1
	s_cbranch_scc1 .Lgp10a_z
	s_add_i32 s32, s2, s66
	s_cmpk_gt_i32 s32, 0x3ff
	s_cbranch_scc1 .Lgp10a_last
	s_ashr_i32 s98, s32, 8
	s_ashr_i32 s99, s2, 8
	s_sub_i32 s98, s98, s99
	s_lshl_b32 s98, s98, 12
	s_and_b32 s99, s32, 63
	s_and_b32 s100, s2, 63
	s_sub_i32 s99, s99, s100
	s_lshl_b32 s99, s99, 6
	s_add_i32 s98, s98, s99
	s_mul_i32 s78, s98, 0x1a00
	s_ashr_i32 s79, s78, 31
	s_bfe_u32 s98, s32, 0x20006
	s_bfe_u32 s99, s2, 0x20006
	s_sub_i32 s98, s98, s99
	s_lshl_b32 s84, s98, 12
	s_ashr_i32 s85, s84, 31
	s_lshl_b32 s86, s98, 9
	s_ashr_i32 s87, s86, 31
	s_waitcnt vmcnt(22)
	s_branch .Lgp10a_go

.Lgp10a_go:
	s_ashr_i32 s10, s2, 8
	s_add_i32 s12, s10, 4
	s_and_b32 s64, s2, 63
	s_ashr_i32 s13, s12, 31
	v_mov_b32_e32 v2, v204
	s_lshl_b64 s[10:11], s[12:13], 12
	s_lshl_b32 s13, s64, 6
	s_or_b32 s10, s10, s13
	v_and_b32_e32 v92, 15, v2
	v_or_b32_e32 v0, s10, v92
	v_mov_b64_e32 v[52:53], s[18:19]
	v_mad_u64_u32 v[52:53], s[14:15], v0, s20, v[52:53]
	v_mad_i32_i24 v53, s11, v102, v53
	v_and_b32_e32 v0, 48, v2
	v_lshl_add_u64 v[52:53], v[52:53], 0, v[0:1]
	v_add_co_u32_e32 v54, vcc, s21, v52
	s_bfe_u32 s13, s2, 0x20006
	s_nop 0
	v_addc_co_u32_e32 v55, vcc, 0, v53, vcc
	v_add_co_u32_e32 v56, vcc, s33, v52
	s_lshl_b32 s16, s13, 7
	s_nop 0
	v_addc_co_u32_e32 v57, vcc, 0, v53, vcc
	v_lshl_add_u64 v[246:247], v[54:55], 0, s[78:79]
	v_mov_b32_e32 v72, v212
	v_mov_b32_e32 v73, v213
	v_mov_b32_e32 v74, v214
	v_mov_b32_e32 v75, v215
	global_load_dwordx4 v[212:215], v[246:247], off offset:2048
	v_lshl_add_u64 v[244:245], v[56:57], 0, s[78:79]
	v_mov_b32_e32 v68, v216
	v_mov_b32_e32 v69, v217
	v_mov_b32_e32 v70, v218
	v_mov_b32_e32 v71, v219
	global_load_dwordx4 v[216:219], v[244:245], off offset:2048
	v_add_co_u32_e32 v54, vcc, s34, v52
	v_ashrrev_i32_e32 v3, 2, v2
	s_nop 0
	v_addc_co_u32_e32 v55, vcc, 0, v53, vcc
	v_add_co_u32_e32 v52, vcc, s35, v52
	v_and_b32_e32 v58, -16, v3
	s_nop 0
	v_addc_co_u32_e32 v53, vcc, 0, v53, vcc
	v_lshl_add_u64 v[246:247], v[54:55], 0, s[78:79]
	v_mov_b32_e32 v60, v220
	v_mov_b32_e32 v61, v221
	v_mov_b32_e32 v62, v222
	v_mov_b32_e32 v63, v223
	global_load_dwordx4 v[220:223], v[246:247], off offset:2048
	s_nop 0
	v_lshl_add_u64 v[244:245], v[52:53], 0, s[78:79]
	v_mov_b32_e32 v52, v224
	v_mov_b32_e32 v53, v225
	v_mov_b32_e32 v54, v226
	v_mov_b32_e32 v55, v227
	global_load_dwordx4 v[224:227], v[244:245], off offset:2048
	v_or_b32_e32 v3, s16, v92
	v_and_b32_e32 v94, 63, v2
	v_add_u32_e32 v64, v3, v58
	v_and_b32_e32 v56, 16, v2
	v_mov_b32_e32 v57, v1
	v_lshl_add_u64 v[66:67], s[30:31], 0, v[56:57]
	v_cmp_lt_u32_e32 vcc, 31, v94
	v_cmp_gt_u32_e64 s[10:11], 32, v94
	v_mov_b32_e32 v56, 0
	v_ashrrev_i32_e32 v65, 31, v64
	v_mov_b32_e32 v76, 0
	v_mov_b32_e32 v77, 0
	v_mov_b32_e32 v78, 0
	v_mov_b32_e32 v79, 0
	s_and_saveexec_b64 s[14:15], s[10:11]
	s_cbranch_execz .LBB0_1439
	v_lshlrev_b64 v[76:77], 5, v[64:65]
	v_lshl_add_u64 v[76:77], v[66:67], 0, v[76:77]
	v_lshl_add_u64 v[246:247], v[76:77], 0, s[84:85]
	v_mov_b32_e32 v76, v228
	v_mov_b32_e32 v77, v229
	v_mov_b32_e32 v78, v230
	v_mov_b32_e32 v79, v231
	global_load_dwordx4 v[228:231], v[246:247], off
.LBB0_1439:
	s_or_b64 exec, exec, s[14:15]
	s_lshl_b32 s10, s16, 2
	s_add_u32 s10, s24, s10
	v_bfe_u32 v93, v2, 4, 2
	s_addc_u32 s11, s25, 0
	v_ashrrev_i32_e32 v59, 31, v58
	v_lshl_add_u64 v[58:59], v[58:59], 2, s[10:11]
	v_lshlrev_b32_e32 v80, 4, v93
	v_mov_b32_e32 v81, v1
	v_lshl_add_u64 v[84:85], v[58:59], 0, v[80:81]
	v_lshl_add_u64 v[244:245], v[84:85], 0, s[86:87]
	v_mov_b32_e32 v80, v232
	v_mov_b32_e32 v81, v233
	v_mov_b32_e32 v82, v234
	v_mov_b32_e32 v83, v235
	global_load_dwordx4 v[232:235], v[244:245], off
	v_mov_b32_e32 v57, 0
	v_mov_b32_e32 v58, 0
	v_mov_b32_e32 v59, 0
	s_and_saveexec_b64 s[10:11], vcc
	s_cbranch_execz .LBB0_1441
	v_lshlrev_b64 v[56:57], 5, v[64:65]
	v_lshl_add_u64 v[56:57], v[66:67], 0, v[56:57]
	v_add_co_u32_e32 v56, vcc, 0x4000, v56
	s_nop 1
	v_addc_co_u32_e32 v57, vcc, 0, v57, vcc
	v_lshl_add_u64 v[246:247], v[56:57], 0, s[84:85]
	v_mov_b32_e32 v56, v240
	v_mov_b32_e32 v57, v241
	v_mov_b32_e32 v58, v242
	v_mov_b32_e32 v59, v243
	global_load_dwordx4 v[240:243], v[246:247], off

.Lgp10a_d:
	v_ashrrev_i32_e32 v3, 31, v2
	v_lshrrev_b32_e32 v84, 27, v3
	v_add_u32_e32 v84, v2, v84
	v_lshrrev_b32_e32 v85, 5, v84
	v_and_b32_e32 v84, 0xfffffe0, v84
	v_sub_u32_e32 v84, v2, v84
	v_mul_lo_u32 v85, v85, s48
	v_lshlrev_b32_e32 v84, 4, v84
	v_add3_u32 v84, 0, v85, v84
	ds_write_b128 v84, v[4:7] offset:51200
	v_add_u32_e32 v84, 0x200, v2
	v_ashrrev_i32_e32 v85, 31, v84
	v_lshrrev_b32_e32 v85, 27, v85
	v_add_u32_e32 v85, v84, v85
	v_lshrrev_b32_e32 v86, 5, v85
	v_and_b32_e32 v85, 0xfffffe0, v85
	v_sub_u32_e32 v84, v84, v85
	v_mul_lo_u32 v85, v86, s48
	v_lshlrev_b32_e32 v84, 4, v84
	v_add3_u32 v84, 0, v85, v84
	ds_write_b128 v84, v[8:11] offset:51200
	v_add_u32_e32 v84, 0x400, v2
	v_ashrrev_i32_e32 v85, 31, v84
	v_lshrrev_b32_e32 v85, 27, v85
	v_add_u32_e32 v85, v84, v85
	v_lshrrev_b32_e32 v86, 5, v85
	v_and_b32_e32 v85, 0xfffffe0, v85
	v_sub_u32_e32 v84, v84, v85
	v_mul_lo_u32 v85, v86, s48
	v_lshlrev_b32_e32 v84, 4, v84
	v_add3_u32 v84, 0, v85, v84
	ds_write_b128 v84, v[12:15] offset:51200
	v_add_u32_e32 v84, 0x600, v2
	v_ashrrev_i32_e32 v85, 31, v84
	v_lshrrev_b32_e32 v85, 27, v85
	v_add_u32_e32 v85, v84, v85
	v_lshrrev_b32_e32 v86, 5, v85
	v_and_b32_e32 v85, 0xfffffe0, v85
	v_sub_u32_e32 v84, v84, v85
	s_lshl_b32 s10, s12, 3
	s_lshl_b32 s11, s13, 1
	v_mul_lo_u32 v85, v86, s48
	v_lshlrev_b32_e32 v84, 4, v84
	s_or_b32 s56, s10, s11
	v_add3_u32 v84, 0, v85, v84
	s_cmp_gt_i32 s56, 44
	s_mov_b64 s[10:11], -1
	ds_write_b128 v84, v[16:19] offset:51200
	s_cbranch_scc0 .LBB0_1447
	s_cmp_gt_u32 s56, 60
	s_cbranch_scc0 .LBB0_1444
	s_sub_i32 s26, s56, 61
	s_mov_b64 s[10:11], 0
	s_mov_b64 s[58:59], s[18:19]
	s_mov_b64 s[60:61], s[26:27]

.LBB0_1449:
	v_lshlrev_b32_e32 v86, 2, v2
	v_and_b32_e32 v87, 0x1fc, v86
	v_add_u32_e32 v104, 0, v87
	v_add_u32_e32 v107, s92, v86
	v_add_u32_e32 v106, s92, v87
	s_nop 0
	v_mfma_f32_16x16x32_bf16 v[86:89], v[76:79], v[72:75], 0
	v_lshlrev_b32_e32 v84, 9, v92
	v_and_b32_e32 v85, 0xffffffc0, v2
	v_add3_u32 v85, 0, v84, v85
	v_add_u32_e32 v108, v85, v0
	v_ashrrev_i32_e32 v84, 7, v2
	s_nop 0
	s_nop 1
	v_add_f32_e32 v90, v80, v86
	v_add_f32_e32 v87, v81, v87
	v_min_f32_e32 v86, 0, v90
	v_mul_f32_e64 v90, |v90|, s49
	v_mul_f32_e64 v91, |v87|, s49
	v_add_f32_e32 v95, v82, v88
	v_add_f32_e32 v89, v83, v89
	v_exp_f32_e32 v90, v90
	v_exp_f32_e32 v91, v91
	v_min_f32_e32 v88, 0, v95
	v_mul_f32_e64 v95, |v95|, s49
	v_mul_f32_e64 v96, |v89|, s49
	v_exp_f32_e32 v95, v95
	v_exp_f32_e32 v96, v96
	v_add_f32_e32 v90, 1.0, v90
	v_add_f32_e32 v91, 1.0, v91
	v_log_f32_e32 v90, v90
	v_log_f32_e32 v91, v91
	v_add_f32_e32 v95, 1.0, v95
	v_add_f32_e32 v96, 1.0, v96
	v_log_f32_e32 v95, v95
	v_log_f32_e32 v96, v96
	v_min_f32_e32 v87, 0, v87
	v_xor_b32_e32 v91, 0x80000000, v91
	v_xor_b32_e32 v90, 0x80000000, v90
	v_min_f32_e32 v89, 0, v89
	v_pk_fma_f32 v[86:87], v[90:91], s[52:53], v[86:87] op_sel_hi:[1,0,1]
	v_xor_b32_e32 v91, 0x80000000, v96
	v_xor_b32_e32 v90, 0x80000000, v95
	v_pk_fma_f32 v[88:89], v[90:91], s[52:53], v[88:89] op_sel_hi:[1,0,1]
	v_pk_mul_f32 v[86:87], v[86:87], s[54:55] op_sel_hi:[1,0]
	v_pk_mul_f32 v[88:89], v[88:89], s[54:55] op_sel_hi:[1,0]
	ds_write_b128 v108, v[86:89]
	v_mfma_f32_16x16x32_bf16 v[86:89], v[76:79], v[68:71], 0
	v_lshlrev_b32_e32 v105, 13, v84
	v_cmp_lt_i32_e64 s[10:11], 0, v84
	v_mov_b32_e32 v117, 0
	s_nop 4
	v_add_f32_e32 v85, v81, v87
	v_mul_f32_e64 v87, |v85|, s49
	v_exp_f32_e32 v90, v87
	v_add_f32_e32 v0, v80, v86
	v_min_f32_e32 v87, 0, v85
	v_min_f32_e32 v86, 0, v0
	v_add_f32_e32 v85, 1.0, v90
	v_add_f32_e32 v90, v82, v88
	v_mul_f32_e64 v0, |v0|, s49
	v_min_f32_e32 v88, 0, v90
	v_mul_f32_e64 v90, |v90|, s49
	v_add_f32_e32 v89, v83, v89
	v_exp_f32_e32 v0, v0
	v_exp_f32_e32 v90, v90
	v_mul_f32_e64 v91, |v89|, s49
	v_exp_f32_e32 v91, v91
	v_add_f32_e32 v0, 1.0, v0
	v_add_f32_e32 v90, 1.0, v90
	v_log_f32_e32 v0, v0
	v_log_f32_e32 v85, v85
	v_log_f32_e32 v95, v90
	v_add_f32_e32 v90, 1.0, v91
	v_log_f32_e32 v96, v90
	v_xor_b32_e32 v91, 0x80000000, v85
	v_xor_b32_e32 v90, 0x80000000, v0
	v_min_f32_e32 v89, 0, v89
	v_pk_fma_f32 v[86:87], v[90:91], s[52:53], v[86:87] op_sel_hi:[1,0,1]
	v_xor_b32_e32 v91, 0x80000000, v96
	v_xor_b32_e32 v90, 0x80000000, v95
	v_pk_fma_f32 v[88:89], v[90:91], s[52:53], v[88:89] op_sel_hi:[1,0,1]
	v_pk_mul_f32 v[86:87], v[86:87], s[54:55] op_sel_hi:[1,0]
	v_pk_mul_f32 v[88:89], v[88:89], s[54:55] op_sel_hi:[1,0]
	ds_write_b128 v108, v[86:89] offset:8192
	v_mfma_f32_16x16x32_bf16 v[86:89], v[76:79], v[60:63], 0
	v_mfma_f32_16x16x32_bf16 v[76:79], v[76:79], v[52:55], 0
	s_nop 6
	v_add_f32_e32 v85, v81, v87
	v_mul_f32_e64 v87, |v85|, s49
	v_exp_f32_e32 v90, v87
	v_add_f32_e32 v0, v80, v86
	v_min_f32_e32 v86, 0, v0
	v_mul_f32_e64 v0, |v0|, s49
	v_exp_f32_e32 v0, v0
	v_min_f32_e32 v87, 0, v85
	v_add_f32_e32 v85, 1.0, v90
	v_add_f32_e32 v90, v82, v88
	v_min_f32_e32 v88, 0, v90
	v_mul_f32_e64 v90, |v90|, s49
	v_add_f32_e32 v89, v83, v89
	v_exp_f32_e32 v90, v90
	v_mul_f32_e64 v91, |v89|, s49
	v_add_f32_e32 v0, 1.0, v0
	v_exp_f32_e32 v91, v91
	v_log_f32_e32 v0, v0
	v_add_f32_e32 v90, 1.0, v90
	v_log_f32_e32 v95, v90
	v_add_f32_e32 v90, 1.0, v91
	v_log_f32_e32 v96, v90
	v_xor_b32_e32 v90, 0x80000000, v0
	v_add_f32_e32 v0, v80, v76
	v_add_f32_e32 v77, v81, v77
	v_add_f32_e32 v81, v82, v78
	v_min_f32_e32 v76, 0, v0
	v_mul_f32_e64 v0, |v0|, s49
	v_mul_f32_e64 v80, |v77|, s49
	v_min_f32_e32 v78, 0, v81
	v_mul_f32_e64 v81, |v81|, s49
	v_add_f32_e32 v79, v83, v79
	v_exp_f32_e32 v0, v0
	v_exp_f32_e32 v80, v80
	v_exp_f32_e32 v81, v81
	v_mul_f32_e64 v82, |v79|, s49
	v_exp_f32_e32 v82, v82
	v_add_f32_e32 v0, 1.0, v0
	v_add_f32_e32 v80, 1.0, v80
	v_add_f32_e32 v81, 1.0, v81
	v_log_f32_e32 v85, v85
	v_log_f32_e32 v0, v0
	v_log_f32_e32 v80, v80
	v_log_f32_e32 v83, v81
	v_add_f32_e32 v81, 1.0, v82
	v_log_f32_e32 v82, v81
	v_xor_b32_e32 v91, 0x80000000, v85
	v_min_f32_e32 v77, 0, v77
	v_xor_b32_e32 v81, 0x80000000, v80
	v_xor_b32_e32 v80, 0x80000000, v0
	v_min_f32_e32 v89, 0, v89
	v_pk_fma_f32 v[86:87], v[90:91], s[52:53], v[86:87] op_sel_hi:[1,0,1]
	v_xor_b32_e32 v91, 0x80000000, v96
	v_xor_b32_e32 v90, 0x80000000, v95
	v_min_f32_e32 v79, 0, v79
	v_pk_fma_f32 v[76:77], v[80:81], s[52:53], v[76:77] op_sel_hi:[1,0,1]
	v_xor_b32_e32 v81, 0x80000000, v82
	v_xor_b32_e32 v80, 0x80000000, v83
	v_pk_fma_f32 v[88:89], v[90:91], s[52:53], v[88:89] op_sel_hi:[1,0,1]
	v_pk_fma_f32 v[78:79], v[80:81], s[52:53], v[78:79] op_sel_hi:[1,0,1]
	v_pk_mul_f32 v[88:89], v[88:89], s[54:55] op_sel_hi:[1,0]
	v_pk_mul_f32 v[86:87], v[86:87], s[54:55] op_sel_hi:[1,0]
	v_pk_mul_f32 v[78:79], v[78:79], s[54:55] op_sel_hi:[1,0]
	v_pk_mul_f32 v[76:77], v[76:77], s[54:55] op_sel_hi:[1,0]
	v_add_u32_e32 v0, v104, v105
	ds_write_b128 v108, v[86:89] offset:16384
	ds_write_b128 v108, v[76:79] offset:24576
	s_waitcnt lgkmcnt(0)
	s_barrier
	ds_read2st64_b32 v[76:77], v0 offset1:2
	ds_read2st64_b32 v[78:79], v0 offset0:4 offset1:6
	ds_read2st64_b32 v[80:81], v0 offset0:8 offset1:10
	ds_read2st64_b32 v[82:83], v0 offset0:12 offset1:14
	ds_read2st64_b32 v[86:87], v0 offset0:16 offset1:18
	ds_read2st64_b32 v[88:89], v0 offset0:20 offset1:22
	ds_read2st64_b32 v[90:91], v0 offset0:24 offset1:26
	ds_read2st64_b32 v[118:119], v0 offset0:28 offset1:30
	s_waitcnt lgkmcnt(7)
	v_add_f32_e32 v115, 0, v76
	v_add_f32_e32 v116, v115, v77
	s_waitcnt lgkmcnt(6)
	v_add_f32_e32 v113, v116, v78
	v_add_f32_e32 v114, v113, v79
	s_waitcnt lgkmcnt(5)
	v_add_f32_e32 v111, v114, v80
	v_add_f32_e32 v112, v111, v81
	s_waitcnt lgkmcnt(4)
	v_add_f32_e32 v101, v112, v82
	v_add_f32_e32 v109, v101, v83
	s_waitcnt lgkmcnt(3)
	v_add_f32_e32 v99, v109, v86
	v_add_f32_e32 v100, v99, v87
	s_waitcnt lgkmcnt(2)
	v_add_f32_e32 v97, v100, v88
	v_add_f32_e32 v98, v97, v89
	s_waitcnt lgkmcnt(1)
	v_add_f32_e32 v95, v98, v90
	v_add_f32_e32 v96, v95, v91
	s_waitcnt lgkmcnt(0)
	v_add_f32_e32 v90, v96, v118
	v_add_f32_e32 v91, v90, v119
	ds_write_b32 v107, v91
	s_waitcnt lgkmcnt(0)
	s_barrier
	s_and_saveexec_b64 s[12:13], s[10:11]
	s_cbranch_execnz .LBB0_1504
	s_or_b64 exec, exec, s[12:13]
	v_cmp_lt_i32_e64 s[14:15], 1, v84
	s_and_saveexec_b64 s[12:13], s[14:15]
	s_cbranch_execnz .LBB0_1505

.LBB0_1472:
.Lgp10b_top:
	s_cmp_eq_u32 s82, 1
	s_cbranch_scc1 .Lgp10b_z
	s_add_i32 s32, s71, s66
	s_cmpk_gt_i32 s32, 0x3ff
	s_cbranch_scc1 .Lgp10b_last
	s_ashr_i32 s98, s32, 8
	s_ashr_i32 s99, s71, 8
	s_sub_i32 s98, s98, s99
	s_lshl_b32 s98, s98, 12
	s_and_b32 s99, s32, 63
	s_and_b32 s100, s71, 63
	s_sub_i32 s99, s99, s100
	s_lshl_b32 s99, s99, 6
	s_add_i32 s98, s98, s99
	s_mul_i32 s78, s98, 0x1a00
	s_ashr_i32 s79, s78, 31
	s_bfe_u32 s98, s32, 0x20006
	s_bfe_u32 s99, s71, 0x20006
	s_sub_i32 s98, s98, s99
	s_lshl_b32 s84, s98, 12
	s_ashr_i32 s85, s84, 31
	s_lshl_b32 s86, s98, 9
	s_ashr_i32 s87, s86, 31
	s_waitcnt vmcnt(22)
	s_branch .Lgp10b_go

.Lgp10b_go:
	s_ashr_i32 s2, s71, 8
	s_add_i32 s12, s2, 4
	s_and_b32 s64, s71, 63
	s_ashr_i32 s13, s12, 31
	v_mov_b32_e32 v2, v204
	s_lshl_b64 s[10:11], s[12:13], 12
	s_lshl_b32 s2, s64, 6
	s_or_b32 s2, s10, s2
	v_and_b32_e32 v92, 15, v2
	v_or_b32_e32 v0, s2, v92
	v_mov_b64_e32 v[52:53], s[18:19]
	v_mad_u64_u32 v[52:53], s[14:15], v0, s20, v[52:53]
	v_mad_i32_i24 v53, s11, v102, v53
	v_and_b32_e32 v0, 48, v2
	v_lshl_add_u64 v[52:53], v[52:53], 0, v[0:1]
	v_add_co_u32_e32 v54, vcc, s21, v52
	s_bfe_u32 s2, s71, 0x20006
	s_nop 0
	v_addc_co_u32_e32 v55, vcc, 0, v53, vcc
	v_add_co_u32_e32 v56, vcc, s33, v52
	s_lshl_b32 s13, s2, 7
	s_nop 0
	v_addc_co_u32_e32 v57, vcc, 0, v53, vcc
	v_lshl_add_u64 v[246:247], v[54:55], 0, s[78:79]
	v_mov_b32_e32 v72, v212
	v_mov_b32_e32 v73, v213
	v_mov_b32_e32 v74, v214
	v_mov_b32_e32 v75, v215
	global_load_dwordx4 v[212:215], v[246:247], off offset:2048
	v_lshl_add_u64 v[244:245], v[56:57], 0, s[78:79]
	v_mov_b32_e32 v68, v216
	v_mov_b32_e32 v69, v217
	v_mov_b32_e32 v70, v218
	v_mov_b32_e32 v71, v219
	global_load_dwordx4 v[216:219], v[244:245], off offset:2048
	v_add_co_u32_e32 v54, vcc, s34, v52
	v_ashrrev_i32_e32 v3, 2, v2
	s_nop 0
	v_addc_co_u32_e32 v55, vcc, 0, v53, vcc
	v_add_co_u32_e32 v52, vcc, s35, v52
	v_and_b32_e32 v58, -16, v3
	s_nop 0
	v_addc_co_u32_e32 v53, vcc, 0, v53, vcc
	v_lshl_add_u64 v[246:247], v[54:55], 0, s[78:79]
	v_mov_b32_e32 v60, v220
	v_mov_b32_e32 v61, v221
	v_mov_b32_e32 v62, v222
	v_mov_b32_e32 v63, v223
	global_load_dwordx4 v[220:223], v[246:247], off offset:2048
	s_nop 0
	v_lshl_add_u64 v[244:245], v[52:53], 0, s[78:79]
	v_mov_b32_e32 v52, v224
	v_mov_b32_e32 v53, v225
	v_mov_b32_e32 v54, v226
	v_mov_b32_e32 v55, v227
	global_load_dwordx4 v[224:227], v[244:245], off offset:2048
	v_or_b32_e32 v3, s13, v92
	v_and_b32_e32 v94, 63, v2
	v_add_u32_e32 v64, v3, v58
	v_and_b32_e32 v56, 16, v2
	v_mov_b32_e32 v57, v1
	v_lshl_add_u64 v[66:67], s[30:31], 0, v[56:57]
	v_cmp_lt_u32_e32 vcc, 31, v94
	v_cmp_gt_u32_e64 s[10:11], 32, v94
	v_mov_b32_e32 v56, 0
	v_ashrrev_i32_e32 v65, 31, v64
	v_mov_b32_e32 v76, 0
	v_mov_b32_e32 v77, 0
	v_mov_b32_e32 v78, 0
	v_mov_b32_e32 v79, 0
	s_and_saveexec_b64 s[14:15], s[10:11]
	s_cbranch_execz .LBB0_1474
	v_lshlrev_b64 v[76:77], 5, v[64:65]
	v_lshl_add_u64 v[76:77], v[66:67], 0, v[76:77]
	v_lshl_add_u64 v[246:247], v[76:77], 0, s[84:85]
	v_mov_b32_e32 v76, v228
	v_mov_b32_e32 v77, v229
	v_mov_b32_e32 v78, v230
	v_mov_b32_e32 v79, v231
	global_load_dwordx4 v[228:231], v[246:247], off
.LBB0_1474:
	s_or_b64 exec, exec, s[14:15]
	s_lshl_b32 s10, s13, 2
	s_add_u32 s10, s24, s10
	v_bfe_u32 v93, v2, 4, 2
	s_addc_u32 s11, s25, 0
	v_ashrrev_i32_e32 v59, 31, v58
	v_lshl_add_u64 v[58:59], v[58:59], 2, s[10:11]
	v_lshlrev_b32_e32 v80, 4, v93
	v_mov_b32_e32 v81, v1
	v_lshl_add_u64 v[84:85], v[58:59], 0, v[80:81]
	v_lshl_add_u64 v[244:245], v[84:85], 0, s[86:87]
	v_mov_b32_e32 v80, v232
	v_mov_b32_e32 v81, v233
	v_mov_b32_e32 v82, v234
	v_mov_b32_e32 v83, v235
	global_load_dwordx4 v[232:235], v[244:245], off
	v_mov_b32_e32 v57, 0
	v_mov_b32_e32 v58, 0
	v_mov_b32_e32 v59, 0
	s_and_saveexec_b64 s[10:11], vcc
	s_cbranch_execz .LBB0_1476
	v_lshlrev_b64 v[56:57], 5, v[64:65]
	v_lshl_add_u64 v[56:57], v[66:67], 0, v[56:57]
	v_add_co_u32_e32 v56, vcc, 0x4000, v56
	s_nop 1
	v_addc_co_u32_e32 v57, vcc, 0, v57, vcc
	v_lshl_add_u64 v[246:247], v[56:57], 0, s[84:85]
	v_mov_b32_e32 v56, v240
	v_mov_b32_e32 v57, v241
	v_mov_b32_e32 v58, v242
	v_mov_b32_e32 v59, v243
	global_load_dwordx4 v[240:243], v[246:247], off

.Lgp10b_d:
	v_ashrrev_i32_e32 v3, 31, v2
	v_lshrrev_b32_e32 v84, 27, v3
	v_add_u32_e32 v84, v2, v84
	v_lshrrev_b32_e32 v85, 5, v84
	v_and_b32_e32 v84, 0xfffffe0, v84
	v_sub_u32_e32 v84, v2, v84
	v_mul_lo_u32 v85, v85, s48
	v_lshlrev_b32_e32 v84, 4, v84
	v_add3_u32 v84, 0, v85, v84
	ds_write_b128 v84, v[20:23] offset:51200
	v_add_u32_e32 v84, 0x200, v2
	v_ashrrev_i32_e32 v85, 31, v84
	v_lshrrev_b32_e32 v85, 27, v85
	v_add_u32_e32 v85, v84, v85
	v_lshrrev_b32_e32 v86, 5, v85
	v_and_b32_e32 v85, 0xfffffe0, v85
	v_sub_u32_e32 v84, v84, v85
	v_mul_lo_u32 v85, v86, s48
	v_lshlrev_b32_e32 v84, 4, v84
	v_add3_u32 v84, 0, v85, v84
	ds_write_b128 v84, v[24:27] offset:51200
	v_add_u32_e32 v84, 0x400, v2
	v_ashrrev_i32_e32 v85, 31, v84
	v_lshrrev_b32_e32 v85, 27, v85
	v_add_u32_e32 v85, v84, v85
	v_lshrrev_b32_e32 v86, 5, v85
	v_and_b32_e32 v85, 0xfffffe0, v85
	v_sub_u32_e32 v84, v84, v85
	v_mul_lo_u32 v85, v86, s48
	v_lshlrev_b32_e32 v84, 4, v84
	v_add3_u32 v84, 0, v85, v84
	ds_write_b128 v84, v[36:39] offset:51200
	v_add_u32_e32 v84, 0x600, v2
	v_ashrrev_i32_e32 v85, 31, v84
	v_lshrrev_b32_e32 v85, 27, v85
	v_add_u32_e32 v85, v84, v85
	v_lshrrev_b32_e32 v86, 5, v85
	v_and_b32_e32 v85, 0xfffffe0, v85
	v_sub_u32_e32 v84, v84, v85
	s_lshl_b32 s10, s12, 3
	s_lshl_b32 s2, s2, 1
	v_mul_lo_u32 v85, v86, s48
	v_lshlrev_b32_e32 v84, 4, v84
	s_or_b32 s56, s10, s2
	v_add3_u32 v84, 0, v85, v84
	s_cmp_gt_i32 s56, 44
	s_mov_b64 s[10:11], -1
	ds_write_b128 v84, v[40:43] offset:51200
	s_cbranch_scc0 .LBB0_1482
	s_cmp_gt_u32 s56, 60
	s_cbranch_scc0 .LBB0_1479
	s_sub_i32 s26, s56, 61
	s_mov_b64 s[10:11], 0
	s_mov_b64 s[58:59], s[18:19]
	s_mov_b64 s[60:61], s[26:27]
